# attention PV section: V-fragment reads issued before the softmax into free VGPRs, re-pack moves dropped
# baseline (speedup 1.0000x reference)
; #define LAS __attribute__((address_space(3)))
; __device__ __forceinline__ unsigned cvt_pk_bf16(float lo, float hi) { unsigned r; asm volatile("v_cvt_pk_bf16_f32 %0, %1, %2" : "=v"(r) : "v"(lo), "v"(hi)); return r; }
; __device__ __forceinline__ void attn_item(const Args& a, LAS unsigned char* lds, int item, int tid, int wave, int lane) {
;     ...
;         float mx = sink;
; #pragma unroll
;         for (int t = 0; t < 9; ++t) mx = fmaxf(mx, fmaxf(fmaxf(s[t][0], s[t][1]), fmaxf(s[t][2], s[t][3])));
;         mx = fmaxf(mx, __shfl_xor(mx, 16)); mx = fmaxf(mx, __shfl_xor(mx, 32));
;         const float nmx2 = -mx * LOG2E;
;         float sum = 0.f;
; #pragma unroll
;         for (int t = 0; t < 9; ++t)
; #pragma unroll
;             for (int i = 0; i < 4; ++i) { const float p = __builtin_amdgcn_exp2f(__builtin_fmaf(s[t][i], LOG2E, nmx2)); s[t][i] = p; sum += p; }
;         sum += __shfl_xor(sum, 16); sum += __shfl_xor(sum, 32);
;         const float inv = __builtin_amdgcn_rcpf(sum + __builtin_amdgcn_exp2f(__builtin_fmaf(sink, LOG2E, nmx2)));
;         bf16x8 pf[5];
; #pragma unroll
;         for (int ks = 0; ks < 5; ++ks) {
;             u32x4 w; w.x = cvt_pk_bf16(s[2 * ks][0], s[2 * ks][1]); w.y = cvt_pk_bf16(s[2 * ks][2], s[2 * ks][3]);
;             if (ks < 4) { w.z = cvt_pk_bf16(s[2 * ks + 1][0], s[2 * ks + 1][1]); w.w = cvt_pk_bf16(s[2 * ks + 1][2], s[2 * ks + 1][3]); } else { w.z = 0u; w.w = 0u; }
;             pf[ks] = __builtin_bit_cast(bf16x8, w);
;         }
;         f32x4 o[4];
; #pragma unroll
;         for (int dt = 0; dt < 4; ++dt) {
;             f32x4 acc = (f32x4){0.f, 0.f, 0.f, 0.f};
;             const LAS bf16_t* vp = VT + (16 * dt + fr) * VP + 16 * rt + 4 * fq;
; #pragma unroll
;             for (int ks = 0; ks < 5; ++ks) {
;                 u32x4 w; const u32x2 lo = *(const LAS u32x2*)(vp + 32 * ks); w.x = lo.x; w.y = lo.y;
;                 if (ks < 4) { const u32x2 hi2 = *(const LAS u32x2*)(vp + 32 * ks + 16); w.z = hi2.x; w.w = hi2.y; } else { w.z = 0u; w.w = 0u; }
.LBB0_1102:
	v_lshl_add_u32 v246, s45, 1, v101
	v_add_u32_e32 v247, v246, v102
	v_add_u32_e32 v248, v246, v103
	v_add_u32_e32 v249, 0x6800, v247
	v_add_u32_e32 v250, 0x8000, v247
	v_add_u32_e32 v251, 0x100, v247
	v_add_u32_e32 v252, 0x9800, v247
	v_add_u32_e32 v253, 0x6800, v248
	ds_read2_b64 v[160:163], v249 offset0:128 offset1:132
	ds_read2_b64 v[164:167], v249 offset0:136 offset1:140
	ds_read2_b64 v[168:171], v249 offset0:144 offset1:148
	ds_read2_b64 v[172:175], v249 offset0:152 offset1:156
	ds_read2st64_b64 v[176:179], v251 offset0:54 offset1:66
	ds_read2_b64 v[180:183], v250 offset0:164 offset1:168
	ds_read2_b64 v[184:187], v250 offset0:172 offset1:176
	ds_read2_b64 v[188:191], v250 offset0:180 offset1:184
	ds_read2_b64 v[192:195], v250 offset0:188 offset1:192
	ds_read2_b64 v[200:203], v252 offset0:192 offset1:196
	ds_read2_b64 v[204:207], v252 offset0:200 offset1:204
	ds_read2_b64 v[208:211], v252 offset0:208 offset1:212
	v_mov_b32_e32 v196, 0
	v_mov_b32_e32 v197, 0
	v_mov_b32_e32 v218, 0
	v_mov_b32_e32 v219, 0
	v_mov_b32_e32 v238, 0
	v_mov_b32_e32 v239, 0
	v_mov_b32_e32 v242, 0
	v_mov_b32_e32 v243, 0
	v_mov_b32_e32 v38, s41
	v_cndmask_b32_e64 v37, v32, v38, s[12:13]
	v_cndmask_b32_e64 v32, v37, v32, s[14:15]
	v_max_f32_e32 v37, v36, v36
	v_max_f32_e32 v38, v0, v0
	v_max_f32_e32 v37, v38, v37
	v_max_f32_e32 v38, v1, v1
	v_max_f32_e32 v39, v3, v3
	v_max_f32_e32 v38, v39, v38
	v_max3_f32 v37, v40, v37, v38
	v_max_f32_e32 v38, v31, v31
	v_max_f32_e32 v39, v30, v30
	v_max_f32_e32 v38, v39, v38
	v_max_f32_e32 v39, v27, v27
	v_max_f32_e32 v44, v26, v26
	v_max_f32_e32 v39, v44, v39
	v_max3_f32 v38, v28, v29, v38
	v_max3_f32 v39, v24, v25, v39
	v_max3_f32 v37, v37, v38, v39
	v_max_f32_e32 v38, v23, v23
	v_max_f32_e32 v39, v22, v22
	v_max_f32_e32 v38, v39, v38
	v_max_f32_e32 v39, v19, v19
	v_max_f32_e32 v44, v18, v18
	v_max_f32_e32 v39, v44, v39
	v_max3_f32 v38, v20, v21, v38
	v_max3_f32 v39, v16, v17, v39
	v_max3_f32 v37, v37, v38, v39
	v_max_f32_e32 v38, v15, v15
	v_max_f32_e32 v39, v14, v14
	v_max_f32_e32 v38, v39, v38
	v_max_f32_e32 v39, v11, v11
	v_max_f32_e32 v44, v10, v10
	v_max_f32_e32 v39, v44, v39
	v_max3_f32 v38, v12, v13, v38
	v_max3_f32 v39, v8, v9, v39
	v_cndmask_b32_e64 v34, v34, v108, s[16:17]
	v_cndmask_b32_e64 v35, v35, v108, s[18:19]
	v_max3_f32 v37, v37, v38, v39
	v_max_f32_e32 v38, v7, v7
	v_max_f32_e32 v39, v6, v6
	v_max_f32_e32 v38, v39, v38
	v_max_f32_e32 v39, v35, v35
	v_max_f32_e32 v44, v34, v34
	v_cndmask_b32_e64 v33, v108, v33, s[14:15]
	v_max_f32_e32 v39, v44, v39
	v_max3_f32 v38, v4, v5, v38
	v_max3_f32 v39, v32, v33, v39
	v_max3_f32 v37, v37, v38, v39
	ds_bpermute_b32 v38, v41, v37
	v_lshl_add_u32 v71, s45, 1, v101
	v_add_u32_e32 v72, v71, v102
	v_mov_b32_e32 v91, v2
	s_xor_b64 s[36:37], s[36:37], -1
	s_waitcnt lgkmcnt(0)
	v_max_f32_e32 v38, v38, v38
	v_max_f32_e32 v37, v37, v38
	ds_bpermute_b32 v38, v42, v37
	s_waitcnt lgkmcnt(0)
	ds_read2_b64 v[212:215], v252 offset0:216 offset1:220
	ds_read_b64 v[216:217], v247 offset:40704
	ds_read2_b64 v[220:223], v253 offset0:128 offset1:132
	ds_read2_b64 v[224:227], v253 offset0:136 offset1:140
	ds_read2_b64 v[228:231], v253 offset0:144 offset1:148
	ds_read2_b64 v[232:235], v253 offset0:152 offset1:156
	ds_read_b64 v[240:241], v248 offset:27904
	v_max_f32_e32 v38, v38, v38
	v_max_f32_e32 v37, v37, v38
	v_mul_f32_e32 v50, 0xbfb8aa3b, v37
	v_fmamk_f32 v4, v4, 0x3fb8aa3b, v50
	v_fmamk_f32 v0, v0, 0x3fb8aa3b, v50
	v_exp_f32_e32 v63, v4
	v_fmamk_f32 v4, v5, 0x3fb8aa3b, v50
	v_exp_f32_e32 v0, v0
	v_fmamk_f32 v36, v36, 0x3fb8aa3b, v50
	v_exp_f32_e32 v64, v4
	v_fmamk_f32 v4, v6, 0x3fb8aa3b, v50
	v_exp_f32_e32 v36, v36
	v_fmamk_f32 v3, v3, 0x3fb8aa3b, v50
	v_exp_f32_e32 v65, v4
	v_fmamk_f32 v4, v7, 0x3fb8aa3b, v50
	v_exp_f32_e32 v3, v3
	v_fmamk_f32 v1, v1, 0x3fb8aa3b, v50
	v_exp_f32_e32 v66, v4
	v_fmamk_f32 v4, v32, 0x3fb8aa3b, v50
	v_exp_f32_e32 v1, v1
	v_fmamk_f32 v28, v28, 0x3fb8aa3b, v50
	v_fmamk_f32 v24, v24, 0x3fb8aa3b, v50
	v_fmamk_f32 v20, v20, 0x3fb8aa3b, v50
	v_fmamk_f32 v16, v16, 0x3fb8aa3b, v50
	v_fmamk_f32 v12, v12, 0x3fb8aa3b, v50
	v_fmamk_f32 v8, v8, 0x3fb8aa3b, v50
	v_exp_f32_e32 v67, v4
	v_fmamk_f32 v4, v33, 0x3fb8aa3b, v50
	v_add_f32_e32 v37, 0, v0
	v_exp_f32_e32 v28, v28
	v_fmamk_f32 v29, v29, 0x3fb8aa3b, v50
	v_exp_f32_e32 v38, v24
	v_fmamk_f32 v24, v25, 0x3fb8aa3b, v50
	v_exp_f32_e32 v46, v20
	v_fmamk_f32 v20, v21, 0x3fb8aa3b, v50
	v_exp_f32_e32 v51, v16
	v_fmamk_f32 v16, v17, 0x3fb8aa3b, v50
	v_exp_f32_e32 v55, v12
	v_fmamk_f32 v12, v13, 0x3fb8aa3b, v50
	v_exp_f32_e32 v59, v8
	v_fmamk_f32 v8, v9, 0x3fb8aa3b, v50
	v_exp_f32_e32 v68, v4
	v_fmamk_f32 v4, v34, 0x3fb8aa3b, v50
	v_add_f32_e32 v37, v36, v37
	v_exp_f32_e32 v29, v29
	v_fmamk_f32 v30, v30, 0x3fb8aa3b, v50
	v_exp_f32_e32 v39, v24
	v_fmamk_f32 v24, v26, 0x3fb8aa3b, v50
	v_exp_f32_e32 v47, v20
	v_fmamk_f32 v20, v22, 0x3fb8aa3b, v50
	v_exp_f32_e32 v52, v16
	v_fmamk_f32 v16, v18, 0x3fb8aa3b, v50
	v_exp_f32_e32 v56, v12
	v_fmamk_f32 v12, v14, 0x3fb8aa3b, v50
	v_exp_f32_e32 v60, v8
	v_fmamk_f32 v8, v10, 0x3fb8aa3b, v50
	v_exp_f32_e32 v69, v4
	v_fmamk_f32 v4, v35, 0x3fb8aa3b, v50
	v_add_f32_e32 v37, v3, v37
	v_exp_f32_e32 v30, v30
	v_fmamk_f32 v31, v31, 0x3fb8aa3b, v50
	v_exp_f32_e32 v44, v24
	v_fmamk_f32 v24, v27, 0x3fb8aa3b, v50
	v_exp_f32_e32 v48, v20
	v_fmamk_f32 v20, v23, 0x3fb8aa3b, v50
	v_exp_f32_e32 v53, v16
	v_fmamk_f32 v16, v19, 0x3fb8aa3b, v50
	v_exp_f32_e32 v57, v12
	v_fmamk_f32 v12, v15, 0x3fb8aa3b, v50
	v_exp_f32_e32 v61, v8
	v_fmamk_f32 v8, v11, 0x3fb8aa3b, v50
	v_exp_f32_e32 v70, v4
	v_cvt_pk_bf16_f32 v4, v0, v36
	v_cvt_pk_bf16_f32 v5, v3, v1
	v_add_u32_e32 v3, 0x6800, v72
	v_add_f32_e32 v37, v1, v37
	v_exp_f32_e32 v31, v31
	v_exp_f32_e32 v45, v24
	v_exp_f32_e32 v49, v20
	v_exp_f32_e32 v54, v16
	v_exp_f32_e32 v58, v12
	v_exp_f32_e32 v62, v8
	v_cvt_pk_bf16_f32 v6, v28, v29
	v_cvt_pk_bf16_f32 v7, v30, v31
	v_cvt_pk_bf16_f32 v8, v38, v39
	v_cvt_pk_bf16_f32 v9, v44, v45
	v_cvt_pk_bf16_f32 v10, v46, v47
	v_cvt_pk_bf16_f32 v11, v48, v49
	v_cvt_pk_bf16_f32 v12, v51, v52
	v_cvt_pk_bf16_f32 v13, v53, v54
	v_cvt_pk_bf16_f32 v14, v55, v56
	v_cvt_pk_bf16_f32 v15, v57, v58
	v_cvt_pk_bf16_f32 v16, v59, v60
	v_cvt_pk_bf16_f32 v17, v61, v62
	v_cvt_pk_bf16_f32 v18, v63, v64
	v_cvt_pk_bf16_f32 v19, v65, v66
	v_cvt_pk_bf16_f32 v0, v67, v68
	v_cvt_pk_bf16_f32 v1, v69, v70
	v_add_f32_e32 v37, v28, v37
	v_add_f32_e32 v24, v29, v37
	v_add_f32_e32 v24, v30, v24
	v_add_f32_e32 v28, v31, v24
	v_add_f32_e32 v28, v38, v28
	v_add_f32_e32 v28, v39, v28
	v_add_f32_e32 v32, v44, v28
	s_waitcnt lgkmcnt(0)
; #define LAS __attribute__((address_space(3)))
; __device__ __forceinline__ unsigned cvt_pk_bf16(float lo, float hi) { unsigned r; asm volatile("v_cvt_pk_bf16_f32 %0, %1, %2" : "=v"(r) : "v"(lo), "v"(hi)); return r; }
; #define MFMA16(a, b, c) __builtin_amdgcn_mfma_f32_16x16x32_bf16((a), (b), (c), 0, 0, 0)
; __device__ __forceinline__ void attn_item(const Args& a, LAS unsigned char* lds, int item, int tid, int wave, int lane) {
;     ...
;         f32x4 o[4];
; #pragma unroll
;         for (int dt = 0; dt < 4; ++dt) {
;             f32x4 acc = (f32x4){0.f, 0.f, 0.f, 0.f};
;             const LAS bf16_t* vp = VT + (16 * dt + fr) * VP + 16 * rt + 4 * fq;
; #pragma unroll
;             for (int ks = 0; ks < 5; ++ks) {
;                 u32x4 w; const u32x2 lo = *(const LAS u32x2*)(vp + 32 * ks); w.x = lo.x; w.y = lo.y;
;                 if (ks < 4) { const u32x2 hi2 = *(const LAS u32x2*)(vp + 32 * ks + 16); w.z = hi2.x; w.w = hi2.y; } else { w.z = 0u; w.w = 0u; }
;                 acc = MFMA16(__builtin_bit_cast(bf16x8, w), pf[ks], acc);
;             }
;             o[dt] = acc;
;         }
;         bf16_t* op = HO + (rowbase + q0 + 16 * rt + fr) * DM + 512 + (kvh * 4 + g) * 64 + 4 * fq;
; #pragma unroll
;         for (int dt = 0; dt < 4; ++dt) { u32x2 w; w.x = cvt_pk_bf16(o[dt][0] * inv, o[dt][1] * inv); w.y = cvt_pk_bf16(o[dt][2] * inv, o[dt][3] * inv); *(u32x2*)(op + 16 * dt) = w; }
	v_mfma_f32_16x16x32_bf16 v[20:23], v[160:163], v[4:7], 0
	v_add_f32_e32 v32, v45, v32
	v_add_f32_e32 v32, v46, v32
	v_add_f32_e32 v32, v47, v32
	s_waitcnt lgkmcnt(0)
	v_mfma_f32_16x16x32_bf16 v[20:23], v[164:167], v[8:11], v[20:23]
	v_add_f32_e32 v3, v48, v32
	v_add_u32_e32 v44, 0x8000, v72
	s_waitcnt lgkmcnt(0)
	v_mfma_f32_16x16x32_bf16 v[20:23], v[168:171], v[12:15], v[20:23]
	v_add_u32_e32 v28, 0x100, v72
	v_add_f32_e32 v3, v49, v3
	s_waitcnt lgkmcnt(0)
	v_mfma_f32_16x16x32_bf16 v[20:23], v[172:175], v[16:19], v[20:23]
	s_waitcnt lgkmcnt(0)
	v_add_f32_e32 v3, v51, v3
	v_add_f32_e32 v36, v52, v3
	v_mov_b32_e32 v3, v2
	v_mov_b32_e32 v236, v176
	v_mov_b32_e32 v237, v177
	s_nop 1
	v_mfma_f32_16x16x32_bf16 v[20:23], v[236:239], v[0:3], v[20:23]
	v_add_f32_e32 v24, v53, v36
	v_add_f32_e32 v45, v54, v24
	s_waitcnt lgkmcnt(0)
	s_waitcnt lgkmcnt(0)
	v_mfma_f32_16x16x32_bf16 v[28:31], v[178:181], v[4:7], 0
	s_waitcnt lgkmcnt(0)
	v_mfma_f32_16x16x32_bf16 v[28:31], v[182:185], v[8:11], v[28:31]
	v_add_f32_e32 v36, v55, v45
	v_add_u32_e32 v45, 0x9800, v72
	v_mfma_f32_16x16x32_bf16 v[24:27], v[186:189], v[12:15], v[28:31]
	v_add_f32_e32 v44, v56, v36
	v_add_u32_e32 v49, v71, v103
	v_add_u32_e32 v51, 0x6800, v49
	s_nop 0
	s_waitcnt lgkmcnt(0)
	v_mfma_f32_16x16x32_bf16 v[24:27], v[190:193], v[16:19], v[24:27]
	v_add_f32_e32 v28, v57, v44
	v_add_f32_e32 v44, v58, v28
	v_mfma_f32_16x16x32_bf16 v[24:27], v[194:197], v[0:3], v[24:27]
	v_add_f32_e32 v32, v59, v44
	v_add_f32_e32 v44, v60, v32
	s_waitcnt lgkmcnt(0)
	v_mfma_f32_16x16x32_bf16 v[36:39], v[200:203], v[4:7], 0
	v_add_f32_e32 v44, v61, v44
	v_add_f32_e32 v44, v62, v44
	v_add_f32_e32 v44, v63, v44
	s_waitcnt lgkmcnt(0)
	v_mfma_f32_16x16x32_bf16 v[28:31], v[204:207], v[8:11], v[36:39]
	v_add_f32_e32 v44, v64, v44
	v_add_f32_e32 v48, v65, v44
	v_add_f32_e32 v52, v66, v48
	s_waitcnt lgkmcnt(0)
	v_mfma_f32_16x16x32_bf16 v[28:31], v[208:211], v[12:15], v[28:31]
	s_waitcnt lgkmcnt(0)
	v_mfma_f32_16x16x32_bf16 v[28:31], v[212:215], v[16:19], v[28:31]
	v_fmac_f32_e32 v50, 0x3fb8aa3b, v40
	s_waitcnt lgkmcnt(0)
	v_mfma_f32_16x16x32_bf16 v[28:31], v[216:219], v[0:3], v[28:31]
	v_add_f32_e32 v32, v67, v52
	v_add_f32_e32 v32, v68, v32
	v_add_f32_e32 v52, v69, v32
	s_waitcnt lgkmcnt(0)
	v_mfma_f32_16x16x32_bf16 v[4:7], v[220:223], v[4:7], 0
	v_add_f32_e32 v44, v70, v52
	ds_bpermute_b32 v45, v41, v44
	s_waitcnt lgkmcnt(0)
	v_mfma_f32_16x16x32_bf16 v[4:7], v[224:227], v[8:11], v[4:7]
	v_mov_b32_e32 v51, v2
	s_waitcnt lgkmcnt(0)
	v_add_f32_e32 v36, v44, v45
	v_mfma_f32_16x16x32_bf16 v[4:7], v[228:231], v[12:15], v[4:7]
	ds_bpermute_b32 v12, v42, v36
	v_exp_f32_e32 v13, v50
	v_mov_b32_e32 v50, v2
	s_waitcnt lgkmcnt(0)
	v_mfma_f32_16x16x32_bf16 v[4:7], v[232:235], v[16:19], v[4:7]
	s_waitcnt lgkmcnt(0)
	v_add_f32_e32 v8, v36, v12
	v_add_f32_e32 v8, v13, v8
	v_mfma_f32_16x16x32_bf16 v[4:7], v[240:243], v[0:3], v[4:7]
	v_or_b32_e32 v0, s45, v43
	v_or_b32_e32 v0, s30, v0
	v_mov_b32_e32 v1, s31
	v_rcp_f32_e32 v3, v8
	v_lshlrev_b64 v[0:1], 11, v[0:1]
	v_lshl_add_u64 v[0:1], s[74:75], 0, v[0:1]
	v_lshl_add_u64 v[0:1], v[0:1], 0, s[22:23]
	v_lshl_add_u64 v[0:1], v[0:1], 0, v[90:91]
	v_lshl_add_u64 v[8:9], v[0:1], 0, s[28:29]
	v_mul_f32_e32 v10, v20, v3
	v_mul_f32_e32 v11, v21, v3
	v_add_co_u32_e32 v0, vcc, s42, v0
	v_cvt_pk_bf16_f32 v10, v10, v11
	v_mul_f32_e32 v11, v22, v3
	s_nop 0
	v_addc_co_u32_e32 v1, vcc, 0, v1, vcc
	v_mul_f32_e32 v12, v23, v3
	v_cvt_pk_bf16_f32 v11, v11, v12
	global_store_dwordx2 v[0:1], v[10:11], off offset:1024
	v_mul_f32_e32 v0, v24, v3
	v_mul_f32_e32 v1, v25, v3
	v_cvt_pk_bf16_f32 v0, v0, v1
	v_mul_f32_e32 v1, v26, v3
	v_mul_f32_e32 v10, v27, v3
	v_cvt_pk_bf16_f32 v1, v1, v10
	global_store_dwordx2 v[8:9], v[0:1], off offset:32
	v_mul_f32_e32 v0, v3, v28
	v_mul_f32_e32 v1, v3, v29
	v_cvt_pk_bf16_f32 v0, v0, v1
	v_mul_f32_e32 v1, v3, v30
	v_mul_f32_e32 v10, v3, v31
	v_cvt_pk_bf16_f32 v1, v1, v10
	global_store_dwordx2 v[8:9], v[0:1], off offset:64
	v_mul_f32_e32 v0, v3, v4
	v_mul_f32_e32 v1, v3, v5
	v_cvt_pk_bf16_f32 v0, v0, v1
	v_mul_f32_e32 v1, v3, v6
	s_mov_b32 s45, 16
	s_andn2_b64 vcc, exec, s[36:37]
	s_mov_b64 s[36:37], 0
	v_mul_f32_e32 v3, v3, v7
	v_cvt_pk_bf16_f32 v1, v1, v3
	global_store_dwordx2 v[8:9], v[0:1], off offset:96
	s_cbranch_vccz .LBB0_1087
